# baseline (speedup 1.0000x reference)
; __device__ __forceinline__ unsigned pack2(float a, float b) { const f32x2_t v = {a, b}; const bf16x2_t r = __builtin_convertvector(v, bf16x2_t); return __builtin_bit_cast(unsigned, r); }
; __device__ __forceinline__ void ph_attn(const Params& p, char* shm) {
;     ...
;     lsum += __shfl_xor(lsum, 16);
;     lsum += __shfl_xor(lsum, 32);
;     const float inv = 1.f / lsum;
;     u16* op = p.OLAT + (size_t)r * 8192 + hd * 512 + g4 * 4;
; #pragma unroll
;     for (int dt = 0; dt < 32; ++dt) {
;       uint2 o = {pack2(O[dt][0] * inv, O[dt][1] * inv), pack2(O[dt][2] * inv, O[dt][3] * inv)};
;       *(uint2*)(op + dt * 16) = o;
;     }
.LBB0_66:
	v_cmp_lt_i32_e32 vcc, v210, v208
	v_readlane_b32 s15, v245, 24
	v_readlane_b32 s4, v245, 62
	v_cndmask_b32_e32 v32, v207, v210, vcc
	v_lshlrev_b32_e32 v32, 2, v32
	ds_bpermute_b32 v32, v32, v224
	v_cmp_lt_i32_e32 vcc, v209, v208
	s_waitcnt lgkmcnt(0)
	v_add_f32_e32 v32, v224, v32
	v_cndmask_b32_e32 v34, v207, v209, vcc
	v_lshlrev_b32_e32 v34, 2, v34
	ds_bpermute_b32 v34, v34, v32
	s_waitcnt lgkmcnt(0)
	v_add_f32_e32 v32, v32, v34
	v_div_scale_f32 v34, s[0:1], v32, v32, 1.0
	v_rcp_f32_e32 v35, v34
	s_nop 0
	v_fma_f32 v132, -v34, v35, 1.0
	v_fmac_f32_e32 v35, v132, v35
	v_div_scale_f32 v132, vcc, 1.0, v32, 1.0
	v_mul_f32_e32 v133, v132, v35
	v_fma_f32 v134, -v34, v133, v132
	v_fmac_f32_e32 v133, v134, v35
	v_fma_f32 v34, -v34, v133, v132
	v_div_fmas_f32 v34, v34, v35, v133
	v_div_fixup_f32 v32, v34, v32, 1.0
	v_pk_mul_f32 v[24:25], v[24:25], v[32:33] op_sel_hi:[1,0]
	v_pk_mul_f32 v[26:27], v[26:27], v[32:33] op_sel_hi:[1,0]
	v_lshl_add_u64 v[34:35], s[6:7], 1, v[200:201]
	v_cvt_pk_bf16_f32 v24, v24, v25
	v_cvt_pk_bf16_f32 v25, v26, v27
	global_store_dwordx2 v[34:35], v[24:25], off offset:736 nt
	v_pk_mul_f32 v[24:25], v[40:41], v[32:33] op_sel_hi:[1,0]
	v_pk_mul_f32 v[26:27], v[42:43], v[32:33] op_sel_hi:[1,0]
	v_cvt_pk_bf16_f32 v24, v24, v25
	v_cvt_pk_bf16_f32 v25, v26, v27
	v_pk_mul_f32 v[128:129], v[128:129], v[32:33] op_sel_hi:[1,0]
	v_pk_mul_f32 v[130:131], v[130:131], v[32:33] op_sel_hi:[1,0]
	v_pk_mul_f32 v[124:125], v[124:125], v[32:33] op_sel_hi:[1,0]
	v_pk_mul_f32 v[126:127], v[126:127], v[32:33] op_sel_hi:[1,0]
	v_pk_mul_f32 v[120:121], v[120:121], v[32:33] op_sel_hi:[1,0]
	v_pk_mul_f32 v[122:123], v[122:123], v[32:33] op_sel_hi:[1,0]
	v_pk_mul_f32 v[116:117], v[116:117], v[32:33] op_sel_hi:[1,0]
	v_pk_mul_f32 v[118:119], v[118:119], v[32:33] op_sel_hi:[1,0]
	v_pk_mul_f32 v[112:113], v[112:113], v[32:33] op_sel_hi:[1,0]
	v_pk_mul_f32 v[114:115], v[114:115], v[32:33] op_sel_hi:[1,0]
	v_pk_mul_f32 v[108:109], v[108:109], v[32:33] op_sel_hi:[1,0]
	v_pk_mul_f32 v[110:111], v[110:111], v[32:33] op_sel_hi:[1,0]
	v_pk_mul_f32 v[104:105], v[104:105], v[32:33] op_sel_hi:[1,0]
	v_pk_mul_f32 v[106:107], v[106:107], v[32:33] op_sel_hi:[1,0]
	v_pk_mul_f32 v[100:101], v[100:101], v[32:33] op_sel_hi:[1,0]
	v_pk_mul_f32 v[102:103], v[102:103], v[32:33] op_sel_hi:[1,0]
	v_pk_mul_f32 v[96:97], v[96:97], v[32:33] op_sel_hi:[1,0]
	v_pk_mul_f32 v[98:99], v[98:99], v[32:33] op_sel_hi:[1,0]
	v_pk_mul_f32 v[92:93], v[92:93], v[32:33] op_sel_hi:[1,0]
	v_pk_mul_f32 v[94:95], v[94:95], v[32:33] op_sel_hi:[1,0]
	v_pk_mul_f32 v[88:89], v[88:89], v[32:33] op_sel_hi:[1,0]
	v_pk_mul_f32 v[90:91], v[90:91], v[32:33] op_sel_hi:[1,0]
	v_pk_mul_f32 v[84:85], v[84:85], v[32:33] op_sel_hi:[1,0]
	v_pk_mul_f32 v[86:87], v[86:87], v[32:33] op_sel_hi:[1,0]
	v_pk_mul_f32 v[80:81], v[80:81], v[32:33] op_sel_hi:[1,0]
	v_pk_mul_f32 v[82:83], v[82:83], v[32:33] op_sel_hi:[1,0]
	v_pk_mul_f32 v[76:77], v[76:77], v[32:33] op_sel_hi:[1,0]
	v_pk_mul_f32 v[78:79], v[78:79], v[32:33] op_sel_hi:[1,0]
	v_pk_mul_f32 v[72:73], v[72:73], v[32:33] op_sel_hi:[1,0]
	v_pk_mul_f32 v[74:75], v[74:75], v[32:33] op_sel_hi:[1,0]
	v_pk_mul_f32 v[68:69], v[68:69], v[32:33] op_sel_hi:[1,0]
	v_pk_mul_f32 v[70:71], v[70:71], v[32:33] op_sel_hi:[1,0]
	v_pk_mul_f32 v[64:65], v[64:65], v[32:33] op_sel_hi:[1,0]
	v_pk_mul_f32 v[66:67], v[66:67], v[32:33] op_sel_hi:[1,0]
	v_pk_mul_f32 v[60:61], v[60:61], v[32:33] op_sel_hi:[1,0]
	v_pk_mul_f32 v[62:63], v[62:63], v[32:33] op_sel_hi:[1,0]
	v_pk_mul_f32 v[56:57], v[56:57], v[32:33] op_sel_hi:[1,0]
	v_pk_mul_f32 v[58:59], v[58:59], v[32:33] op_sel_hi:[1,0]
	v_pk_mul_f32 v[52:53], v[52:53], v[32:33] op_sel_hi:[1,0]
	v_pk_mul_f32 v[54:55], v[54:55], v[32:33] op_sel_hi:[1,0]
	v_pk_mul_f32 v[48:49], v[48:49], v[32:33] op_sel_hi:[1,0]
	v_pk_mul_f32 v[50:51], v[50:51], v[32:33] op_sel_hi:[1,0]
	v_pk_mul_f32 v[44:45], v[44:45], v[32:33] op_sel_hi:[1,0]
	v_pk_mul_f32 v[46:47], v[46:47], v[32:33] op_sel_hi:[1,0]
	v_pk_mul_f32 v[36:37], v[36:37], v[32:33] op_sel_hi:[1,0]
	v_pk_mul_f32 v[38:39], v[38:39], v[32:33] op_sel_hi:[1,0]
	global_store_dwordx2 v[34:35], v[24:25], off offset:768 nt
	v_pk_mul_f32 v[24:25], v[28:29], v[32:33] op_sel_hi:[1,0]
	v_pk_mul_f32 v[26:27], v[30:31], v[32:33] op_sel_hi:[1,0]
	v_pk_mul_f32 v[20:21], v[20:21], v[32:33] op_sel_hi:[1,0]
	v_pk_mul_f32 v[22:23], v[22:23], v[32:33] op_sel_hi:[1,0]
; __device__ __forceinline__ unsigned pack2(float a, float b) { const f32x2_t v = {a, b}; const bf16x2_t r = __builtin_convertvector(v, bf16x2_t); return __builtin_bit_cast(unsigned, r); }
; __device__ __forceinline__ void ph_attn(const Params& p, char* shm) {
;     ...
; #pragma unroll
;     for (int dt = 0; dt < 32; ++dt) {
;       uint2 o = {pack2(O[dt][0] * inv, O[dt][1] * inv), pack2(O[dt][2] * inv, O[dt][3] * inv)};
;       *(uint2*)(op + dt * 16) = o;
;     }
	v_pk_mul_f32 v[16:17], v[16:17], v[32:33] op_sel_hi:[1,0]
	v_pk_mul_f32 v[18:19], v[18:19], v[32:33] op_sel_hi:[1,0]
	v_pk_mul_f32 v[12:13], v[12:13], v[32:33] op_sel_hi:[1,0]
	v_pk_mul_f32 v[14:15], v[14:15], v[32:33] op_sel_hi:[1,0]
	v_pk_mul_f32 v[8:9], v[8:9], v[32:33] op_sel_hi:[1,0]
	v_pk_mul_f32 v[10:11], v[10:11], v[32:33] op_sel_hi:[1,0]
	v_pk_mul_f32 v[4:5], v[4:5], v[32:33] op_sel_hi:[1,0]
	v_pk_mul_f32 v[6:7], v[6:7], v[32:33] op_sel_hi:[1,0]
	v_pk_mul_f32 v[0:1], v[0:1], v[32:33] op_sel_hi:[1,0]
	v_pk_mul_f32 v[2:3], v[2:3], v[32:33] op_sel_hi:[1,0]
	v_cvt_pk_bf16_f32 v128, v128, v129
	v_cvt_pk_bf16_f32 v129, v130, v131
	v_cvt_pk_bf16_f32 v124, v124, v125
	v_cvt_pk_bf16_f32 v125, v126, v127
	v_cvt_pk_bf16_f32 v120, v120, v121
	v_cvt_pk_bf16_f32 v121, v122, v123
	v_cvt_pk_bf16_f32 v116, v116, v117
	v_cvt_pk_bf16_f32 v117, v118, v119
	v_cvt_pk_bf16_f32 v112, v112, v113
	v_cvt_pk_bf16_f32 v113, v114, v115
	v_cvt_pk_bf16_f32 v108, v108, v109
	v_cvt_pk_bf16_f32 v109, v110, v111
	v_cvt_pk_bf16_f32 v104, v104, v105
	v_cvt_pk_bf16_f32 v105, v106, v107
	v_cvt_pk_bf16_f32 v100, v100, v101
	v_cvt_pk_bf16_f32 v101, v102, v103
	v_cvt_pk_bf16_f32 v96, v96, v97
	v_cvt_pk_bf16_f32 v97, v98, v99
	v_cvt_pk_bf16_f32 v92, v92, v93
	v_cvt_pk_bf16_f32 v93, v94, v95
	v_cvt_pk_bf16_f32 v88, v88, v89
	v_cvt_pk_bf16_f32 v89, v90, v91
	v_cvt_pk_bf16_f32 v84, v84, v85
	v_cvt_pk_bf16_f32 v85, v86, v87
	v_cvt_pk_bf16_f32 v80, v80, v81
	v_cvt_pk_bf16_f32 v81, v82, v83
	v_cvt_pk_bf16_f32 v76, v76, v77
	v_cvt_pk_bf16_f32 v77, v78, v79
	v_cvt_pk_bf16_f32 v72, v72, v73
	v_cvt_pk_bf16_f32 v73, v74, v75
	v_cvt_pk_bf16_f32 v68, v68, v69
	v_cvt_pk_bf16_f32 v69, v70, v71
	v_cvt_pk_bf16_f32 v64, v64, v65
	v_cvt_pk_bf16_f32 v65, v66, v67
	v_cvt_pk_bf16_f32 v60, v60, v61
	v_cvt_pk_bf16_f32 v61, v62, v63
	v_cvt_pk_bf16_f32 v56, v56, v57
	v_cvt_pk_bf16_f32 v57, v58, v59
	v_cvt_pk_bf16_f32 v52, v52, v53
	v_cvt_pk_bf16_f32 v53, v54, v55
	v_cvt_pk_bf16_f32 v48, v48, v49
	v_cvt_pk_bf16_f32 v49, v50, v51
	v_cvt_pk_bf16_f32 v44, v44, v45
	v_cvt_pk_bf16_f32 v45, v46, v47
	v_cvt_pk_bf16_f32 v36, v36, v37
	v_cvt_pk_bf16_f32 v37, v38, v39
	v_cvt_pk_bf16_f32 v24, v24, v25
	v_cvt_pk_bf16_f32 v25, v26, v27
	v_cvt_pk_bf16_f32 v20, v20, v21
	v_cvt_pk_bf16_f32 v21, v22, v23
	v_cvt_pk_bf16_f32 v16, v16, v17
	v_cvt_pk_bf16_f32 v17, v18, v19
	v_cvt_pk_bf16_f32 v12, v12, v13
	v_cvt_pk_bf16_f32 v13, v14, v15
	v_cvt_pk_bf16_f32 v8, v8, v9
	v_cvt_pk_bf16_f32 v9, v10, v11
	v_cvt_pk_bf16_f32 v4, v4, v5
	v_cvt_pk_bf16_f32 v5, v6, v7
	v_cvt_pk_bf16_f32 v0, v0, v1
	v_cvt_pk_bf16_f32 v1, v2, v3
	global_store_dwordx2 v[34:35], v[128:129], off nt
	global_store_dwordx2 v[34:35], v[124:125], off offset:32 nt
	global_store_dwordx2 v[34:35], v[120:121], off offset:64 nt
	global_store_dwordx2 v[34:35], v[116:117], off offset:96 nt
	global_store_dwordx2 v[34:35], v[112:113], off offset:128 nt
	global_store_dwordx2 v[34:35], v[108:109], off offset:160 nt
	global_store_dwordx2 v[34:35], v[104:105], off offset:192 nt
	global_store_dwordx2 v[34:35], v[100:101], off offset:224 nt
	global_store_dwordx2 v[34:35], v[96:97], off offset:256 nt
	global_store_dwordx2 v[34:35], v[92:93], off offset:288 nt
	global_store_dwordx2 v[34:35], v[88:89], off offset:320 nt
	global_store_dwordx2 v[34:35], v[84:85], off offset:352 nt
	global_store_dwordx2 v[34:35], v[80:81], off offset:384 nt
	global_store_dwordx2 v[34:35], v[76:77], off offset:416 nt
	global_store_dwordx2 v[34:35], v[72:73], off offset:448 nt
	global_store_dwordx2 v[34:35], v[68:69], off offset:480 nt
	global_store_dwordx2 v[34:35], v[64:65], off offset:512 nt
	global_store_dwordx2 v[34:35], v[60:61], off offset:544 nt
	global_store_dwordx2 v[34:35], v[56:57], off offset:576 nt
	global_store_dwordx2 v[34:35], v[52:53], off offset:608 nt
	global_store_dwordx2 v[34:35], v[48:49], off offset:640 nt
	global_store_dwordx2 v[34:35], v[44:45], off offset:672 nt
	global_store_dwordx2 v[34:35], v[36:37], off offset:704 nt
	global_store_dwordx2 v[34:35], v[24:25], off offset:800 nt
	global_store_dwordx2 v[34:35], v[20:21], off offset:832 nt
	global_store_dwordx2 v[34:35], v[16:17], off offset:864 nt
	global_store_dwordx2 v[34:35], v[12:13], off offset:896 nt
	global_store_dwordx2 v[34:35], v[8:9], off offset:928 nt
	global_store_dwordx2 v[34:35], v[4:5], off offset:960 nt
	global_store_dwordx2 v[34:35], v[0:1], off offset:992 nt

; #define LDSP(TY, p) ((__attribute__((address_space(3))) TY*)(p))
; #define WAIT_L0() asm volatile("s_waitcnt lgkmcnt(0)" ::: "memory")
; __device__ __forceinline__ void ph_attn(const Params& p, char* shm) {
;     ...
;     const int t = r & (L - 1), b = r >> 13;
;     const int cnt = min(t + 1, 256), nchunk = (cnt + 15) >> 4;
;     const u16* ckvb = p.CKV + (size_t)b * L * 512;
;     __attribute__((address_space(3))) int* idxl = LDSP(int, wb + 16640);
;     if (t >= 256) { WAIT_L0(); topk_row(p, r, lane, idxl); }
;     s16x8 qb[16];
;     const u16* qp = p.QLAT + (size_t)r * 8192 + hd * 512 + g4 * 8;
; #pragma unroll
;     for (int ks = 0; ks < 16; ++ks) qb[ks] = *(const s16x8*)(qp + ks * 32);
;     f32x4 O[32];
; #pragma unroll
;     for (int dt = 0; dt < 32; ++dt) O[dt] = f32x4{0.f, 0.f, 0.f, 0.f};
;     float mref = -INFINITY, lsum = 0.f;
.LBB0_902:
	v_readlane_b32 s6, v244, 0
	v_readlane_b32 s7, v244, 1
	s_lshl_b64 s[0:1], s[6:7], 14
	v_lshl_add_u64 v[0:1], v[196:197], 0, s[0:1]
	global_load_dwordx4 v[132:135], v[0:1], off nt
	global_load_dwordx4 v[136:139], v[0:1], off offset:64 nt
	global_load_dwordx4 v[140:143], v[0:1], off offset:128 nt
	global_load_dwordx4 v[144:147], v[0:1], off offset:192 nt
	global_load_dwordx4 v[148:151], v[0:1], off offset:256 nt
	global_load_dwordx4 v[152:155], v[0:1], off offset:320 nt
	global_load_dwordx4 v[156:159], v[0:1], off offset:384 nt
	global_load_dwordx4 v[160:163], v[0:1], off offset:448 nt
	global_load_dwordx4 v[164:167], v[0:1], off offset:512 nt
	global_load_dwordx4 v[168:171], v[0:1], off offset:576 nt
	global_load_dwordx4 v[172:175], v[0:1], off offset:640 nt
	global_load_dwordx4 v[176:179], v[0:1], off offset:704 nt
	global_load_dwordx4 v[180:183], v[0:1], off offset:768 nt
	global_load_dwordx4 v[184:187], v[0:1], off offset:832 nt
	global_load_dwordx4 v[188:191], v[0:1], off offset:896 nt
	global_load_dwordx4 v[192:195], v[0:1], off offset:960 nt
	s_ashr_i32 s0, s6, 13
	s_min_u32 s4, s15, 0xff
	s_ashr_i32 s1, s0, 31
	v_mov_b32_e32 v32, v33
	v_mov_b32_e32 v34, v33
	v_mov_b32_e32 v35, v33
	s_add_i32 s15, s4, 16
	s_lshl_b64 s[0:1], s[0:1], 23
	v_mov_b64_e32 v[24:25], v[32:33]
	v_mov_b64_e32 v[38:39], v[34:35]
	v_mov_b64_e32 v[46:47], v[34:35]
	v_mov_b64_e32 v[50:51], v[34:35]
	v_mov_b64_e32 v[54:55], v[34:35]
	v_mov_b64_e32 v[58:59], v[34:35]
	v_mov_b64_e32 v[62:63], v[34:35]
	v_mov_b64_e32 v[66:67], v[34:35]
	v_mov_b64_e32 v[70:71], v[34:35]
	v_mov_b64_e32 v[74:75], v[34:35]
	v_mov_b64_e32 v[78:79], v[34:35]
	v_mov_b64_e32 v[82:83], v[34:35]
	v_mov_b64_e32 v[86:87], v[34:35]
	v_mov_b64_e32 v[90:91], v[34:35]
	v_mov_b64_e32 v[94:95], v[34:35]
	v_mov_b64_e32 v[98:99], v[34:35]
	v_mov_b64_e32 v[102:103], v[34:35]
	v_mov_b64_e32 v[106:107], v[34:35]
	v_mov_b64_e32 v[110:111], v[34:35]
	v_mov_b64_e32 v[114:115], v[34:35]
	v_mov_b64_e32 v[118:119], v[34:35]
	v_mov_b64_e32 v[122:123], v[34:35]
	v_mov_b64_e32 v[126:127], v[34:35]
	v_mov_b64_e32 v[130:131], v[34:35]
	v_mov_b64_e32 v[42:43], v[34:35]
	v_mov_b64_e32 v[28:29], v[32:33]
	v_mov_b64_e32 v[20:21], v[32:33]
	v_mov_b64_e32 v[16:17], v[32:33]
	v_mov_b64_e32 v[12:13], v[32:33]
	v_mov_b64_e32 v[8:9], v[32:33]
	v_mov_b64_e32 v[4:5], v[32:33]
	v_mov_b64_e32 v[0:1], v[32:33]
	s_lshl_b64 s[6:7], s[6:7], 13
	v_lshl_add_u64 v[202:203], v[198:199], 0, s[0:1]
	s_and_b32 s15, s15, 0x1f0
	v_mov_b32_e32 v224, 0
	v_mov_b32_e32 v228, 0xff800000
	v_mov_b32_e32 v225, v219
	v_mov_b32_e32 v226, v221
	v_mov_b32_e32 v227, v220
	v_mov_b64_e32 v[26:27], v[34:35]
	v_mov_b64_e32 v[36:37], v[32:33]
	v_mov_b64_e32 v[44:45], v[32:33]
	v_mov_b64_e32 v[48:49], v[32:33]
	v_mov_b64_e32 v[52:53], v[32:33]
	v_mov_b64_e32 v[56:57], v[32:33]
	v_mov_b64_e32 v[60:61], v[32:33]
	v_mov_b64_e32 v[64:65], v[32:33]
	v_mov_b64_e32 v[68:69], v[32:33]
	v_mov_b64_e32 v[72:73], v[32:33]
	v_mov_b64_e32 v[76:77], v[32:33]
	v_mov_b64_e32 v[80:81], v[32:33]
	v_mov_b64_e32 v[84:85], v[32:33]
	v_mov_b64_e32 v[88:89], v[32:33]
	v_mov_b64_e32 v[92:93], v[32:33]
	v_mov_b64_e32 v[96:97], v[32:33]
	v_mov_b64_e32 v[100:101], v[32:33]
	v_mov_b64_e32 v[104:105], v[32:33]
	v_mov_b64_e32 v[108:109], v[32:33]
	v_mov_b64_e32 v[112:113], v[32:33]
	v_mov_b64_e32 v[116:117], v[32:33]
	v_mov_b64_e32 v[120:121], v[32:33]
	v_mov_b64_e32 v[124:125], v[32:33]
	v_mov_b64_e32 v[128:129], v[32:33]
	v_mov_b64_e32 v[40:41], v[32:33]
	v_mov_b64_e32 v[30:31], v[34:35]
	v_mov_b64_e32 v[22:23], v[34:35]
	v_mov_b64_e32 v[18:19], v[34:35]
	v_mov_b64_e32 v[14:15], v[34:35]
	v_mov_b64_e32 v[10:11], v[34:35]
	v_mov_b64_e32 v[6:7], v[34:35]
	v_mov_b64_e32 v[2:3], v[34:35]
	s_waitcnt vmcnt(0)
	s_branch .LBB0_904

; #define WAIT_L0() asm volatile("s_waitcnt lgkmcnt(0)" ::: "memory")
; __device__ __forceinline__ void ph_indexer(const Params& p, char* shm) {
;     ...
;       const int chunk = side ? 511 - cp : cp;
;       const int t0 = chunk * 16, nst = (t0 + 16 + 127) >> 7;
;       const size_t rowb = (size_t)b * L + t0;
;       const u16* kib = p.KI + (size_t)b * L * 128;
;       s16x8 Aq[2][8];
; #pragma unroll
;       for (int q = 0; q < 2; ++q) {
;         const u16* qp = p.P + (rowb + wid * 2 + q) * NP + QI_OFF + col * 128 + half * 8;
; #pragma unroll
;         for (int s2 = 0; s2 < 8; ++s2) Aq[q][s2] = *(const s16x8*)(qp + s2 * 16);
;       }
;       WAIT_L0();
;       __builtin_amdgcn_s_barrier();
;       {
;         if (tid < 256) {
;           const float2 wf = ((const float2*)(p.WF + rowb * 32))[tid];
;           h16x2 hv; hv[0] = (_Float16)wf.x; hv[1] = (_Float16)wf.y;
;           ((h16x2*)wtab)[tid] = hv;
;         }
.LBB0_917:
	s_ashr_i32 s2, s38, 8
	s_lshl_b32 s3, s38, 4
	s_and_b32 s39, s3, 0xff0
	s_ashr_i32 s3, s2, 31
	s_lshl_b64 s[14:15], s[2:3], 13
	s_or_b32 s8, s14, s39
	s_add_u32 s16, s8, s24
	s_addc_u32 s17, s15, s25
	s_mul_i32 s4, s17, 0x7600
	s_mul_hi_u32 s9, s16, 0x7600
	v_readlane_b32 s52, v245, 25
	s_add_i32 s9, s9, s4
	s_mul_i32 s4, s16, 0x7600
	v_readlane_b32 s62, v245, 35
	v_readlane_b32 s63, v245, 36
	s_add_u32 s10, s62, s4
	s_addc_u32 s11, s63, s9
	v_lshlrev_b32_e32 v128, 1, v114
	v_mov_b32_e32 v129, v33
	v_lshl_add_u64 v[0:1], s[10:11], 0, v[128:129]
	s_mov_b64 s[10:11], 0x2400
	v_lshl_add_u64 v[2:3], v[0:1], 0, s[10:11]
	s_mov_b64 s[10:11], 0x3400
	v_lshl_add_u64 v[4:5], v[0:1], 0, s[10:11]
	global_load_dwordx4 v[74:77], v[2:3], off nt
	global_load_dwordx4 v[50:53], v[2:3], off offset:64 nt
	global_load_dwordx4 v[54:57], v[2:3], off offset:128 nt
	global_load_dwordx4 v[58:61], v[2:3], off offset:192 nt
	global_load_dwordx4 v[62:65], v[4:5], off nt
	global_load_dwordx4 v[66:69], v[4:5], off offset:64 nt
	global_load_dwordx4 v[70:73], v[4:5], off offset:128 nt
	global_load_dwordx4 v[78:81], v[4:5], off offset:192 nt
	s_mov_b64 s[10:11], 0x9a00
	v_lshl_add_u64 v[2:3], v[0:1], 0, s[10:11]
	s_mov_b64 s[10:11], 0xaa00
	v_lshl_add_u64 v[4:5], v[0:1], 0, s[10:11]
	global_load_dwordx4 v[106:109], v[2:3], off nt
	global_load_dwordx4 v[82:85], v[2:3], off offset:64 nt
	global_load_dwordx4 v[86:89], v[2:3], off offset:128 nt
	global_load_dwordx4 v[90:93], v[2:3], off offset:192 nt
	global_load_dwordx4 v[94:97], v[4:5], off nt
	global_load_dwordx4 v[98:101], v[4:5], off offset:64 nt
	global_load_dwordx4 v[102:105], v[4:5], off offset:128 nt
	global_load_dwordx4 v[110:113], v[4:5], off offset:192 nt
	v_readlane_b32 s53, v245, 26
	s_waitcnt lgkmcnt(0)
	v_readlane_b32 s54, v245, 27
	v_readlane_b32 s55, v245, 28
	v_readlane_b32 s56, v245, 29
	v_readlane_b32 s57, v245, 30
	v_readlane_b32 s58, v245, 31
	v_readlane_b32 s59, v245, 32
	v_readlane_b32 s60, v245, 33
	v_readlane_b32 s61, v245, 34
	v_readlane_b32 s64, v245, 37
	v_readlane_b32 s65, v245, 38
	v_readlane_b32 s66, v245, 39
	v_readlane_b32 s67, v245, 40
	s_barrier
	s_and_saveexec_b64 s[10:11], s[0:1]
	s_cbranch_execz .LBB0_919
	s_mov_b32 s9, s15
	s_lshl_b64 s[8:9], s[8:9], 7
	v_lshl_add_u64 v[0:1], v[122:123], 0, s[8:9]
	global_load_dwordx2 v[0:1], v[0:1], off
	s_waitcnt vmcnt(0)
	v_cvt_pk_f16_f32 v0, v0, v1
	ds_write_b32 v115, v0

; #define WAIT_L0() asm volatile("s_waitcnt lgkmcnt(0)" ::: "memory")
; __device__ __forceinline__ void ph_indexer(const Params& p, char* shm) {
;     ...
;       const int chunk = side ? 511 - cp : cp;
;       const int t0 = chunk * 16, nst = (t0 + 16 + 127) >> 7;
;       const size_t rowb = (size_t)b * L + t0;
;       const u16* kib = p.KI + (size_t)b * L * 128;
;       s16x8 Aq[2][8];
; #pragma unroll
;       for (int q = 0; q < 2; ++q) {
;         const u16* qp = p.P + (rowb + wid * 2 + q) * NP + QI_OFF + col * 128 + half * 8;
; #pragma unroll
;         for (int s2 = 0; s2 < 8; ++s2) Aq[q][s2] = *(const s16x8*)(qp + s2 * 16);
;       }
;       WAIT_L0();
;       __builtin_amdgcn_s_barrier();
;       {
;         if (tid < 256) {
;           const float2 wf = ((const float2*)(p.WF + rowb * 32))[tid];
;           h16x2 hv; hv[0] = (_Float16)wf.x; hv[1] = (_Float16)wf.y;
;           ((h16x2*)wtab)[tid] = hv;
;         }
.LBB0_932:
	s_xor_b32 s3, s39, 0x1ff0
	s_or_b32 s14, s14, s3
	s_add_u32 s16, s14, s24
	s_addc_u32 s17, s15, s25
	s_mul_i32 s4, s17, 0x7600
	s_mul_hi_u32 s9, s16, 0x7600
	v_readlane_b32 s52, v245, 25
	s_add_i32 s9, s9, s4
	s_mul_i32 s4, s16, 0x7600
	v_readlane_b32 s62, v245, 35
	v_readlane_b32 s63, v245, 36
	s_add_u32 s18, s62, s4
	s_addc_u32 s19, s63, s9
	v_mov_b32_e32 v129, v33
	v_lshl_add_u64 v[0:1], s[18:19], 0, v[128:129]
	s_mov_b64 s[18:19], 0x2400
	v_lshl_add_u64 v[2:3], v[0:1], 0, s[18:19]
	s_mov_b64 s[18:19], 0x3400
	v_lshl_add_u64 v[4:5], v[0:1], 0, s[18:19]
	global_load_dwordx4 v[58:61], v[2:3], off nt
	global_load_dwordx4 v[16:19], v[2:3], off offset:64 nt
	global_load_dwordx4 v[20:23], v[2:3], off offset:128 nt
	global_load_dwordx4 v[24:27], v[2:3], off offset:192 nt
	global_load_dwordx4 v[28:31], v[4:5], off nt
	global_load_dwordx4 v[50:53], v[4:5], off offset:64 nt
	global_load_dwordx4 v[54:57], v[4:5], off offset:128 nt
	global_load_dwordx4 v[62:65], v[4:5], off offset:192 nt
	s_mov_b64 s[18:19], 0x9a00
	v_lshl_add_u64 v[2:3], v[0:1], 0, s[18:19]
	s_mov_b64 s[18:19], 0xaa00
	v_lshl_add_u64 v[4:5], v[0:1], 0, s[18:19]
	global_load_dwordx4 v[90:93], v[2:3], off nt
	global_load_dwordx4 v[66:69], v[2:3], off offset:64 nt
	global_load_dwordx4 v[70:73], v[2:3], off offset:128 nt
	global_load_dwordx4 v[74:77], v[2:3], off offset:192 nt
	global_load_dwordx4 v[78:81], v[4:5], off nt
	global_load_dwordx4 v[82:85], v[4:5], off offset:64 nt
	global_load_dwordx4 v[86:89], v[4:5], off offset:128 nt
	global_load_dwordx4 v[94:97], v[4:5], off offset:192 nt
	v_readlane_b32 s53, v245, 26
	s_waitcnt lgkmcnt(0)
	v_readlane_b32 s54, v245, 27
	v_readlane_b32 s55, v245, 28
	v_readlane_b32 s56, v245, 29
	v_readlane_b32 s57, v245, 30
	v_readlane_b32 s58, v245, 31
	v_readlane_b32 s59, v245, 32
	v_readlane_b32 s60, v245, 33
	v_readlane_b32 s61, v245, 34
	v_readlane_b32 s64, v245, 37
	v_readlane_b32 s65, v245, 38
	v_readlane_b32 s66, v245, 39
	v_readlane_b32 s67, v245, 40
	s_barrier
	s_and_saveexec_b64 s[18:19], s[0:1]
	s_cbranch_execz .LBB0_934
	s_lshl_b64 s[14:15], s[14:15], 7
	v_lshl_add_u64 v[0:1], v[122:123], 0, s[14:15]
	global_load_dwordx2 v[0:1], v[0:1], off
	s_waitcnt vmcnt(0)
	v_cvt_pk_f16_f32 v0, v0, v1
	ds_write_b32 v115, v0
